# gate/up epilogue: 128 ds_bpermute conv-tap exchanges per wave replaced by DPP row_ror movs (no LDS round trips), hazard-padded
# speedup vs baseline: 1.0111x; 1.0055x over previous
; __device__ __forceinline__ unsigned cvt_pk_bf16(float lo, float hi) { unsigned r; asm volatile("v_cvt_pk_bf16_f32 %0, %1, %2" : "=v"(r) : "v"(lo), "v"(hi)); return r; }
;     __device__ __forceinline__ void operator()(const f32x4 (&acc)[2][2][4][2], const Unit& u, int wr, int wc, int fr, int fq) const {
;     ...
;         for (int n = 0; n < 2; ++n) { w0[n] = *(const f32x4*)(cw + f0 + 4 * n); w1[n] = *(const f32x4*)(cw + dff + f0 + 4 * n); w2[n] = *(const f32x4*)(cw + 2 * dff + f0 + 4 * n); bb[n] = *(const f32x4*)(cb + f0 + 4 * n); }
; #pragma unroll
;         for (int ai = 0; ai < 2; ++ai) {
;             const int rowb = u.pm * BM + ai * HALF + wr * 64, blk = rowb >> 6;
; #pragma unroll
;             for (int m = 0; m < 4; ++m) {
;                 u32x4 wa, wg, wu;
; #pragma unroll
;                 for (int n = 0; n < 2; ++n) {
;                     const f32x4 g = acc[ai][0][m][n], uu = acc[ai][1][m][n], gp = acc[ai][0][m > 0 ? m - 1 : 0][n];
;                     f32x4 r;
; #pragma unroll
;                     for (int e = 0; e < 4; ++e) {
;                         const float s1 = (fr == 15) ? gp[e] : g[e], s2 = (fr >= 14) ? gp[e] : g[e];
;                         const float p1 = __int_as_float(__builtin_amdgcn_ds_bpermute(src1, __float_as_int(s1))), p2 = __int_as_float(__builtin_amdgcn_ds_bpermute(src2, __float_as_int(s2)));
;                         const float c = bb[n][e] + w0[n][e] * p2 + w1[n][e] * p1 + w2[n][e] * g[e];
;                         r[e] = c * uu[e] * __builtin_amdgcn_rcpf(1.0f + __builtin_amdgcn_exp2f(c * -1.4426950408889634f));
;                     }
;                     if (n == 0) { wa.x = cvt_pk_bf16(r[0], r[1]); wa.y = cvt_pk_bf16(r[2], r[3]); wg.x = cvt_pk_bf16(g[0], g[1]); wg.y = cvt_pk_bf16(g[2], g[3]); wu.x = cvt_pk_bf16(uu[0], uu[1]); wu.y = cvt_pk_bf16(uu[2], uu[3]); }
;                     else { wa.z = cvt_pk_bf16(r[0], r[1]); wa.w = cvt_pk_bf16(r[2], r[3]); wg.z = cvt_pk_bf16(g[0], g[1]); wg.w = cvt_pk_bf16(g[2], g[3]); wu.z = cvt_pk_bf16(uu[0], uu[1]); wu.w = cvt_pk_bf16(uu[2], uu[3]); }
;                 }
;                 if (m == 0 && fr < 2) {
;                     *(u32x4*)(hg + (size_t)(blk * 4 + 2 + fr) * dff + f0) = wg; *(u32x4*)(hu + (size_t)(blk * 2 + fr) * dff + f0) = wu;
.LBB0_482:
	v_lshl_or_b32 v196, s45, 7, v216
	v_ashrrev_i32_e32 v197, 31, v196
	v_lshlrev_b64 v[66:67], 2, v[196:197]
	v_lshl_add_u64 v[70:71], s[24:25], 0, v[66:67]
	v_lshl_add_u64 v[72:73], s[38:39], 0, v[66:67]
	v_lshl_add_u64 v[90:91], s[42:43], 0, v[66:67]
	v_lshl_add_u64 v[102:103], s[26:27], 0, v[66:67]
	global_load_dwordx4 v[66:69], v[70:71], off offset:16
	global_load_dwordx4 v[86:89], v[70:71], off
	global_load_dwordx4 v[78:81], v[72:73], off offset:16
	global_load_dwordx4 v[94:97], v[72:73], off
	global_load_dwordx4 v[74:77], v[90:91], off offset:16
	s_nop 0
	global_load_dwordx4 v[90:93], v[90:91], off
	s_nop 0
	global_load_dwordx4 v[70:73], v[102:103], off offset:16
	s_nop 0
	global_load_dwordx4 v[102:105], v[102:103], off
	v_mov_b32_dpp v163, v150 row_ror:2 row_mask:0xf bank_mask:0xf
	v_mov_b32_dpp v167, v152 row_ror:2 row_mask:0xf bank_mask:0xf
	v_mov_b32_dpp v162, v150 row_ror:1 row_mask:0xf bank_mask:0xf
	v_mov_b32_dpp v165, v151 row_ror:2 row_mask:0xf bank_mask:0xf
	v_mov_b32_dpp v166, v152 row_ror:1 row_mask:0xf bank_mask:0xf
	v_mov_b32_dpp v169, v153 row_ror:2 row_mask:0xf bank_mask:0xf
	v_mov_b32_dpp v164, v151 row_ror:1 row_mask:0xf bank_mask:0xf
	v_mov_b32_dpp v168, v153 row_ror:1 row_mask:0xf bank_mask:0xf
	v_mov_b32_dpp v220, v149 row_ror:2 row_mask:0xf bank_mask:0xf
	v_mov_b32_dpp v219, v149 row_ror:1 row_mask:0xf bank_mask:0xf
	s_waitcnt vmcnt(0) lgkmcnt(0)
	v_fma_f32 v220, v69, v220, v73
	v_fma_f32 v167, v88, v167, v104
	v_fma_f32 v163, v86, v163, v102
	v_fma_f32 v169, v89, v169, v105
	v_fmac_f32_e32 v167, v96, v166
	v_fma_f32 v165, v87, v165, v103
	v_fmac_f32_e32 v163, v94, v162
	v_fmac_f32_e32 v169, v97, v168
	v_fmac_f32_e32 v167, v152, v92
	v_fmac_f32_e32 v165, v95, v164
	v_fmac_f32_e32 v163, v150, v90
	v_fmac_f32_e32 v169, v153, v93
	v_mul_f32_e32 v166, v160, v167
	v_mul_f32_e32 v167, 0xbfb8aa3b, v167
	v_fmac_f32_e32 v165, v151, v91
	v_mul_f32_e32 v162, v158, v163
	v_mul_f32_e32 v163, 0xbfb8aa3b, v163
	v_mul_f32_e32 v168, v161, v169
	v_mul_f32_e32 v169, 0xbfb8aa3b, v169
	v_exp_f32_e32 v167, v167
	v_mul_f32_e32 v164, v159, v165
	v_mul_f32_e32 v165, 0xbfb8aa3b, v165
	v_exp_f32_e32 v163, v163
	v_exp_f32_e32 v169, v169
	v_exp_f32_e32 v165, v165
	v_add_f32_e32 v167, 1.0, v167
	v_add_f32_e32 v163, 1.0, v163
	v_add_f32_e32 v169, 1.0, v169
	v_rcp_f32_e32 v167, v167
	v_add_f32_e32 v165, 1.0, v165
	v_rcp_f32_e32 v163, v163
	v_rcp_f32_e32 v169, v169
	v_rcp_f32_e32 v165, v165
	v_mul_f32_e32 v167, v166, v167
	v_mul_f32_e32 v162, v162, v163
	v_mul_f32_e32 v168, v168, v169
	v_mul_f32_e32 v164, v164, v165
	v_cvt_pk_bf16_f32 v166, v162, v164
	v_cvt_pk_bf16_f32 v167, v167, v168
	v_cvt_pk_bf16_f32 v162, v150, v151
	v_cvt_pk_bf16_f32 v163, v152, v153
	v_cvt_pk_bf16_f32 v158, v158, v159
	v_cvt_pk_bf16_f32 v159, v160, v161
	v_mov_b32_dpp v161, v146 row_ror:2 row_mask:0xf bank_mask:0xf
	v_mov_b32_dpp v165, v147 row_ror:2 row_mask:0xf bank_mask:0xf
	v_mov_b32_dpp v169, v148 row_ror:2 row_mask:0xf bank_mask:0xf
	v_mov_b32_dpp v160, v146 row_ror:1 row_mask:0xf bank_mask:0xf
	v_mov_b32_dpp v164, v147 row_ror:1 row_mask:0xf bank_mask:0xf
	v_mov_b32_dpp v168, v148 row_ror:1 row_mask:0xf bank_mask:0xf
	s_waitcnt lgkmcnt(4)
	v_fma_f32 v165, v67, v165, v71
	s_waitcnt lgkmcnt(3)
	v_fma_f32 v169, v68, v169, v72
	v_fma_f32 v161, v66, v161, v70
	s_waitcnt lgkmcnt(1)
	v_fmac_f32_e32 v165, v79, v164
	s_waitcnt lgkmcnt(0)
	v_fmac_f32_e32 v169, v80, v168
	v_fmac_f32_e32 v161, v78, v160
	v_fmac_f32_e32 v220, v81, v219
	v_fmac_f32_e32 v169, v148, v76
	v_fmac_f32_e32 v165, v147, v75
	v_fmac_f32_e32 v161, v146, v74
	v_fmac_f32_e32 v220, v149, v77
	v_mul_f32_e32 v168, v156, v169
	v_mul_f32_e32 v169, 0xbfb8aa3b, v169
	v_mul_f32_e32 v164, v155, v165
	v_mul_f32_e32 v165, 0xbfb8aa3b, v165
	v_mul_f32_e32 v160, v154, v161
	v_mul_f32_e32 v161, 0xbfb8aa3b, v161
	v_mul_f32_e32 v219, v157, v220
	v_mul_f32_e32 v220, 0xbfb8aa3b, v220
	v_exp_f32_e32 v169, v169
	v_exp_f32_e32 v165, v165
	v_exp_f32_e32 v161, v161
	v_exp_f32_e32 v220, v220
	v_add_f32_e32 v169, 1.0, v169
	v_add_f32_e32 v165, 1.0, v165
	v_add_f32_e32 v161, 1.0, v161
	v_add_f32_e32 v220, 1.0, v220
	v_rcp_f32_e32 v169, v169
	v_rcp_f32_e32 v165, v165
	v_rcp_f32_e32 v161, v161
	v_rcp_f32_e32 v220, v220
	v_mul_f32_e32 v169, v168, v169
	v_mul_f32_e32 v164, v164, v165
	v_mul_f32_e32 v160, v160, v161
	v_mul_f32_e32 v219, v219, v220
	v_cvt_pk_bf16_f32 v168, v160, v164
	v_cvt_pk_bf16_f32 v169, v169, v219
	v_cvt_pk_bf16_f32 v164, v146, v147
	v_cvt_pk_bf16_f32 v165, v148, v149
	v_cvt_pk_bf16_f32 v160, v154, v155
	v_cvt_pk_bf16_f32 v161, v156, v157
	s_and_saveexec_b64 s[16:17], s[10:11]
	s_xor_b64 s[56:57], exec, s[16:17]
	v_mov_b64_e32 v[158:159], v[166:167]
	v_mov_b64_e32 v[160:161], v[168:169]
	s_or_saveexec_b64 s[56:57], s[56:57]
	s_lshl_b32 s45, s76, 8
	s_add_i32 s45, s45, s5
	v_or_b32_e32 v156, s45, v170
	s_ashr_i32 s47, s45, 4
	v_mov_b64_e32 v[154:155], s[22:23]
	v_mov_b32_e32 v157, v156
	s_xor_b64 exec, exec, s[56:57]
	s_cbranch_execz .LBB0_486
	s_ashr_i32 s16, s45, 5
	v_or_b32_e32 v166, s47, v215
	v_mov_b64_e32 v[154:155], s[28:29]
	v_or_b32_e32 v157, s16, v170
	v_mad_i64_i32 v[154:155], s[16:17], v166, s78, v[154:155]
	v_lshl_add_u64 v[154:155], v[196:197], 1, v[154:155]
	global_store_dwordx4 v[154:155], v[162:165], off
	v_mov_b64_e32 v[154:155], s[30:31]
; __device__ __forceinline__ unsigned cvt_pk_bf16(float lo, float hi) { unsigned r; asm volatile("v_cvt_pk_bf16_f32 %0, %1, %2" : "=v"(r) : "v"(lo), "v"(hi)); return r; }
;     __device__ __forceinline__ void operator()(const f32x4 (&acc)[2][2][4][2], const Unit& u, int wr, int wc, int fr, int fq) const {
;     ...
;                     const f32x4 g = acc[ai][0][m][n], uu = acc[ai][1][m][n], gp = acc[ai][0][m > 0 ? m - 1 : 0][n];
;                     f32x4 r;
; #pragma unroll
;                     for (int e = 0; e < 4; ++e) {
;                         const float s1 = (fr == 15) ? gp[e] : g[e], s2 = (fr >= 14) ? gp[e] : g[e];
;                         const float p1 = __int_as_float(__builtin_amdgcn_ds_bpermute(src1, __float_as_int(s1))), p2 = __int_as_float(__builtin_amdgcn_ds_bpermute(src2, __float_as_int(s2)));
;                         const float c = bb[n][e] + w0[n][e] * p2 + w1[n][e] * p1 + w2[n][e] * g[e];
;                         r[e] = c * uu[e] * __builtin_amdgcn_rcpf(1.0f + __builtin_amdgcn_exp2f(c * -1.4426950408889634f));
;                     }
;                     if (n == 0) { wa.x = cvt_pk_bf16(r[0], r[1]); wa.y = cvt_pk_bf16(r[2], r[3]); wg.x = cvt_pk_bf16(g[0], g[1]); wg.y = cvt_pk_bf16(g[2], g[3]); wu.x = cvt_pk_bf16(uu[0], uu[1]); wu.y = cvt_pk_bf16(uu[2], uu[3]); }
;                     else { wa.z = cvt_pk_bf16(r[0], r[1]); wa.w = cvt_pk_bf16(r[2], r[3]); wg.z = cvt_pk_bf16(g[0], g[1]); wg.w = cvt_pk_bf16(g[2], g[3]); wu.z = cvt_pk_bf16(uu[0], uu[1]); wu.w = cvt_pk_bf16(uu[2], uu[3]); }
;                 }
;                 if (m == 0 && fr < 2) {
;                     *(u32x4*)(hg + (size_t)(blk * 4 + 2 + fr) * dff + f0) = wg; *(u32x4*)(hu + (size_t)(blk * 2 + fr) * dff + f0) = wu;
;                 } else {
;                     *(u32x4*)(act + (size_t)(rowb + m * 16 + fr) * dff + f0) = wa;
;                 }
;                 if (m == 3 && fr >= 14) *(u32x4*)(hg + (size_t)(blk * 4 + fr - 14) * dff + f0) = wg;
.LBB0_486:
	s_or_b64 exec, exec, s[56:57]
	v_mad_i64_i32 v[162:163], s[16:17], v157, s78, v[154:155]
	v_lshlrev_b64 v[154:155], 1, v[196:197]
	v_lshl_add_u64 v[162:163], v[162:163], 0, v[154:155]
	v_cndmask_b32_e64 v157, v138, v150, s[6:7]
	v_cndmask_b32_e64 v150, v138, v150, s[8:9]
	global_store_dwordx4 v[162:163], v[158:161], off
	s_nop 1
	v_mov_b32_dpp v159, v157 row_ror:1 row_mask:0xf bank_mask:0xf
	v_mov_b32_dpp v157, v150 row_ror:2 row_mask:0xf bank_mask:0xf
	v_cndmask_b32_e64 v150, v139, v151, s[6:7]
	v_cndmask_b32_e64 v151, v139, v151, s[8:9]
	s_nop 1
	v_mov_b32_dpp v161, v150 row_ror:1 row_mask:0xf bank_mask:0xf
	v_cndmask_b32_e64 v150, v140, v152, s[6:7]
	v_cndmask_b32_e64 v152, v140, v152, s[8:9]
	v_mov_b32_dpp v158, v151 row_ror:2 row_mask:0xf bank_mask:0xf
	v_mov_b32_dpp v151, v150 row_ror:1 row_mask:0xf bank_mask:0xf
	v_mov_b32_dpp v160, v152 row_ror:2 row_mask:0xf bank_mask:0xf
	v_cndmask_b32_e64 v150, v141, v153, s[6:7]
	v_cndmask_b32_e64 v152, v141, v153, s[8:9]
	s_nop 1
	v_mov_b32_dpp v153, v150 row_ror:1 row_mask:0xf bank_mask:0xf
	v_mov_b32_dpp v150, v152 row_ror:2 row_mask:0xf bank_mask:0xf
	v_mov_b32_e32 v162, v141
	v_mov_b32_e32 v163, v97
	v_mov_b32_e32 v152, v93
	s_waitcnt lgkmcnt(1)
	v_pk_mul_f32 v[152:153], v[162:163], v[152:153]
	s_waitcnt lgkmcnt(0)
	v_fma_f32 v150, v89, v150, v105
	v_add_f32_e32 v150, v153, v150
	v_add_f32_e32 v162, v152, v150
	v_mul_f32_e32 v150, 0xbfb8aa3b, v162
	v_exp_f32_e32 v163, v150
	v_mov_b32_e32 v152, v140
	v_mov_b32_e32 v153, v96
	v_mov_b32_e32 v150, v92
	v_pk_mul_f32 v[150:151], v[152:153], v[150:151]
	v_fma_f32 v152, v88, v160, v104
	v_add_f32_e32 v151, v151, v152
	v_add_f32_e32 v151, v150, v151
	v_mul_f32_e32 v150, 0xbfb8aa3b, v151
	v_exp_f32_e32 v152, v150
	v_add_f32_e32 v153, 1.0, v163
	v_rcp_f32_e32 v153, v153
	v_mul_f32_e32 v160, v145, v162
	v_add_f32_e32 v152, 1.0, v152
	v_rcp_f32_e32 v152, v152
	v_mul_f32_e32 v151, v144, v151
	v_mul_f32_e32 v162, v160, v153
	v_mov_b32_e32 v153, v95
	v_mul_f32_e32 v151, v151, v152
	v_mov_b32_e32 v152, v139
	v_mov_b32_e32 v160, v91
	v_pk_mul_f32 v[152:153], v[152:153], v[160:161]
	v_fma_f32 v158, v87, v158, v103
	v_add_f32_e32 v153, v153, v158
	v_add_f32_e32 v160, v152, v153
	v_mul_f32_e32 v152, 0xbfb8aa3b, v160
	v_exp_f32_e32 v161, v152
	v_mov_b32_e32 v152, v138
	v_mov_b32_e32 v153, v94
	v_mov_b32_e32 v158, v90
	v_pk_mul_f32 v[152:153], v[152:153], v[158:159]
	v_fma_f32 v157, v86, v157, v102
	v_add_f32_e32 v153, v153, v157
	v_add_f32_e32 v153, v152, v153
	v_mul_f32_e32 v152, 0xbfb8aa3b, v153
	v_exp_f32_e32 v157, v152
	v_add_f32_e32 v158, 1.0, v161
	v_rcp_f32_e32 v158, v158
	v_mul_f32_e32 v159, v143, v160
	v_add_f32_e32 v157, 1.0, v157
	v_rcp_f32_e32 v157, v157
	v_mul_f32_e32 v158, v159, v158
	v_mul_f32_e32 v153, v142, v153
	v_mov_b32_e32 v160, v133
	v_mul_f32_e32 v153, v153, v157
	v_cvt_pk_bf16_f32 v158, v153, v158
	v_cvt_pk_bf16_f32 v159, v151, v162
	v_cvt_pk_bf16_f32 v151, v138, v139
	v_mov_b32_e32 v161, v81
	v_cvt_pk_bf16_f32 v151, v140, v141
	v_cvt_pk_bf16_f32 v142, v142, v143
	v_cndmask_b32_e64 v143, v130, v146, s[8:9]
	v_cvt_pk_bf16_f32 v142, v144, v145
	s_nop 1
	v_mov_b32_dpp v151, v143 row_ror:2 row_mask:0xf bank_mask:0xf
	v_cndmask_b32_e64 v142, v130, v146, s[6:7]
	s_nop 1
	v_mov_b32_dpp v145, v142 row_ror:1 row_mask:0xf bank_mask:0xf
	v_cndmask_b32_e64 v142, v131, v147, s[6:7]
	v_cndmask_b32_e64 v143, v131, v147, s[8:9]
	s_nop 1
	v_mov_b32_dpp v147, v142 row_ror:1 row_mask:0xf bank_mask:0xf
	v_cndmask_b32_e64 v142, v132, v148, s[6:7]
	v_mov_b32_dpp v144, v143 row_ror:2 row_mask:0xf bank_mask:0xf
	v_cndmask_b32_e64 v146, v132, v148, s[8:9]
	v_mov_b32_dpp v143, v142 row_ror:1 row_mask:0xf bank_mask:0xf
	v_cndmask_b32_e64 v142, v133, v149, s[6:7]
	v_cndmask_b32_e64 v148, v133, v149, s[8:9]
	s_nop 1
	v_mov_b32_dpp v149, v142 row_ror:1 row_mask:0xf bank_mask:0xf
	v_mov_b32_dpp v142, v148 row_ror:2 row_mask:0xf bank_mask:0xf
	v_mov_b32_e32 v148, v77
	v_mov_b32_dpp v146, v146 row_ror:2 row_mask:0xf bank_mask:0xf
	s_waitcnt lgkmcnt(4)
	v_fma_f32 v144, v67, v144, v71
	s_waitcnt lgkmcnt(2)
	v_pk_mul_f32 v[148:149], v[160:161], v[148:149]
	s_waitcnt lgkmcnt(1)
	v_fma_f32 v142, v69, v142, v73
	v_add_f32_e32 v142, v149, v142
	v_add_f32_e32 v153, v148, v142
	v_mul_f32_e32 v142, 0xbfb8aa3b, v153
	v_exp_f32_e32 v157, v142
	v_mov_b32_e32 v148, v132
	v_mov_b32_e32 v149, v80
	v_mov_b32_e32 v142, v76
	v_pk_mul_f32 v[142:143], v[148:149], v[142:143]
	s_waitcnt lgkmcnt(0)
	v_fma_f32 v146, v68, v146, v72
	v_add_f32_e32 v143, v143, v146
	v_add_f32_e32 v143, v142, v143
	v_mul_f32_e32 v142, 0xbfb8aa3b, v143
	v_exp_f32_e32 v146, v142
	v_add_f32_e32 v148, 1.0, v157
	v_rcp_f32_e32 v148, v148
	v_mul_f32_e32 v149, v137, v153
	v_add_f32_e32 v146, 1.0, v146
	v_rcp_f32_e32 v146, v146
	v_mul_f32_e32 v143, v136, v143
	v_mul_f32_e32 v153, v149, v148
	v_mov_b32_e32 v148, v131
	v_mul_f32_e32 v143, v143, v146
	v_mov_b32_e32 v149, v79
	v_mov_b32_e32 v146, v75
	v_pk_mul_f32 v[146:147], v[148:149], v[146:147]
	v_mov_b32_e32 v150, v93
	v_add_f32_e32 v144, v147, v144
	v_add_f32_e32 v148, v146, v144
	v_mul_f32_e32 v144, 0xbfb8aa3b, v148
	v_exp_f32_e32 v149, v144
	v_mov_b32_e32 v146, v130
	v_mov_b32_e32 v147, v78
	v_mov_b32_e32 v144, v74
	v_pk_mul_f32 v[144:145], v[146:147], v[144:145]
	v_fma_f32 v146, v66, v151, v70
	v_add_f32_e32 v145, v145, v146
	v_add_f32_e32 v145, v144, v145
	v_mul_f32_e32 v144, 0xbfb8aa3b, v145
	v_exp_f32_e32 v146, v144
	v_add_f32_e32 v147, 1.0, v149
	v_rcp_f32_e32 v147, v147
	v_mul_f32_e32 v145, v134, v145
	v_add_f32_e32 v146, 1.0, v146
	v_rcp_f32_e32 v146, v146
	v_mul_f32_e32 v148, v135, v148
	v_mul_f32_e32 v147, v148, v147
	v_mov_b32_e32 v148, v125
	v_mul_f32_e32 v145, v145, v146
	v_cvt_pk_bf16_f32 v160, v145, v147
	v_cndmask_b32_e64 v145, v125, v141, s[6:7]
	v_cndmask_b32_e64 v141, v125, v141, s[8:9]
	s_nop 1
	v_mov_b32_dpp v147, v145 row_ror:1 row_mask:0xf bank_mask:0xf
	v_mov_b32_dpp v141, v141 row_ror:2 row_mask:0xf bank_mask:0xf
	v_cvt_pk_bf16_f32 v161, v143, v153
	v_cvt_pk_bf16_f32 v143, v130, v131
	v_mov_b32_e32 v149, v97
	v_cvt_pk_bf16_f32 v143, v132, v133
	v_cvt_pk_bf16_f32 v134, v134, v135
	v_mov_b32_e32 v146, v93
	v_cvt_pk_bf16_f32 v134, v136, v137
	v_or_b32_e32 v136, 16, v156
	v_mov_b64_e32 v[134:135], s[22:23]
	v_mad_i64_i32 v[136:137], s[16:17], v136, s78, v[134:135]
	s_waitcnt lgkmcnt(1)
; __device__ __forceinline__ unsigned cvt_pk_bf16(float lo, float hi) { unsigned r; asm volatile("v_cvt_pk_bf16_f32 %0, %1, %2" : "=v"(r) : "v"(lo), "v"(hi)); return r; }
;     __device__ __forceinline__ void operator()(const f32x4 (&acc)[2][2][4][2], const Unit& u, int wr, int wc, int fr, int fq) const {
;     ...
;                     const f32x4 g = acc[ai][0][m][n], uu = acc[ai][1][m][n], gp = acc[ai][0][m > 0 ? m - 1 : 0][n];
;                     f32x4 r;
; #pragma unroll
;                     for (int e = 0; e < 4; ++e) {
;                         const float s1 = (fr == 15) ? gp[e] : g[e], s2 = (fr >= 14) ? gp[e] : g[e];
;                         const float p1 = __int_as_float(__builtin_amdgcn_ds_bpermute(src1, __float_as_int(s1))), p2 = __int_as_float(__builtin_amdgcn_ds_bpermute(src2, __float_as_int(s2)));
;                         const float c = bb[n][e] + w0[n][e] * p2 + w1[n][e] * p1 + w2[n][e] * g[e];
;                         r[e] = c * uu[e] * __builtin_amdgcn_rcpf(1.0f + __builtin_amdgcn_exp2f(c * -1.4426950408889634f));
;                     }
;                     if (n == 0) { wa.x = cvt_pk_bf16(r[0], r[1]); wa.y = cvt_pk_bf16(r[2], r[3]); wg.x = cvt_pk_bf16(g[0], g[1]); wg.y = cvt_pk_bf16(g[2], g[3]); wu.x = cvt_pk_bf16(uu[0], uu[1]); wu.y = cvt_pk_bf16(uu[2], uu[3]); }
;                     else { wa.z = cvt_pk_bf16(r[0], r[1]); wa.w = cvt_pk_bf16(r[2], r[3]); wg.z = cvt_pk_bf16(g[0], g[1]); wg.w = cvt_pk_bf16(g[2], g[3]); wu.z = cvt_pk_bf16(uu[0], uu[1]); wu.w = cvt_pk_bf16(uu[2], uu[3]); }
;                 }
;                 if (m == 0 && fr < 2) {
;                     *(u32x4*)(hg + (size_t)(blk * 4 + 2 + fr) * dff + f0) = wg; *(u32x4*)(hu + (size_t)(blk * 2 + fr) * dff + f0) = wu;
;                 } else {
;                     *(u32x4*)(act + (size_t)(rowb + m * 16 + fr) * dff + f0) = wa;
;                 }
;                 if (m == 3 && fr >= 14) *(u32x4*)(hg + (size_t)(blk * 4 + fr - 14) * dff + f0) = wg;
	v_pk_mul_f32 v[146:147], v[148:149], v[146:147]
	s_waitcnt lgkmcnt(0)
	v_fma_f32 v141, v89, v141, v105
	v_lshl_add_u64 v[136:137], v[136:137], 0, v[154:155]
	v_add_f32_e32 v141, v147, v141
	global_store_dwordx4 v[136:137], v[158:161], off
	v_cndmask_b32_e64 v136, v122, v138, s[6:7]
	v_cndmask_b32_e64 v138, v122, v138, s[8:9]
	v_add_f32_e32 v145, v146, v141
	v_mov_b32_dpp v137, v136 row_ror:1 row_mask:0xf bank_mask:0xf
	v_mov_b32_dpp v143, v138 row_ror:2 row_mask:0xf bank_mask:0xf
	v_cndmask_b32_e64 v136, v123, v139, s[6:7]
	v_cndmask_b32_e64 v138, v123, v139, s[8:9]
	v_mul_f32_e32 v141, 0xbfb8aa3b, v145
	v_mov_b32_dpp v139, v136 row_ror:1 row_mask:0xf bank_mask:0xf
	v_mov_b32_dpp v136, v138 row_ror:2 row_mask:0xf bank_mask:0xf
	v_cndmask_b32_e64 v138, v124, v140, s[6:7]
	v_exp_f32_e32 v146, v141
	v_cndmask_b32_e64 v140, v124, v140, s[8:9]
	v_mov_b32_dpp v141, v138 row_ror:1 row_mask:0xf bank_mask:0xf
	s_nop 1
	v_mov_b32_dpp v138, v140 row_ror:2 row_mask:0xf bank_mask:0xf
	v_add_f32_e32 v140, 1.0, v146
	v_rcp_f32_e32 v148, v140
	v_mov_b32_e32 v146, v124
	v_mov_b32_e32 v147, v96
	v_mov_b32_e32 v140, v92
	s_waitcnt lgkmcnt(1)
	v_pk_mul_f32 v[140:141], v[146:147], v[140:141]
	s_waitcnt lgkmcnt(0)
	v_fma_f32 v138, v88, v138, v104
	v_add_f32_e32 v138, v141, v138
	v_add_f32_e32 v138, v140, v138
	v_mul_f32_e32 v140, 0xbfb8aa3b, v138
	v_exp_f32_e32 v140, v140
	v_mul_f32_e32 v141, v129, v145
	v_mul_f32_e32 v146, v128, v138
	v_mul_f32_e32 v145, v141, v148
	v_add_f32_e32 v138, 1.0, v140
	v_rcp_f32_e32 v147, v138
	v_mov_b32_e32 v140, v123
	v_mov_b32_e32 v141, v95
	v_mov_b32_e32 v138, v91
	v_pk_mul_f32 v[138:139], v[140:141], v[138:139]
	v_fma_f32 v136, v87, v136, v103
	v_add_f32_e32 v136, v139, v136
	v_add_f32_e32 v140, v138, v136
	v_mul_f32_e32 v136, 0xbfb8aa3b, v140
	v_exp_f32_e32 v141, v136
	v_mov_b32_e32 v138, v122
	v_mov_b32_e32 v139, v94
	v_mov_b32_e32 v136, v90
	v_pk_mul_f32 v[136:137], v[138:139], v[136:137]
	v_fma_f32 v138, v86, v143, v102
	v_add_f32_e32 v137, v137, v138
	v_add_f32_e32 v136, v136, v137
	v_mul_f32_e32 v137, 0xbfb8aa3b, v136
	v_exp_f32_e32 v137, v137
	v_add_f32_e32 v139, 1.0, v141
	v_rcp_f32_e32 v139, v139
	v_mul_f32_e32 v136, v126, v136
	v_add_f32_e32 v137, 1.0, v137
	v_rcp_f32_e32 v137, v137
	v_mul_f32_e32 v138, v146, v147
	v_mul_f32_e32 v140, v127, v140
	v_mul_f32_e32 v139, v140, v139
	v_mul_f32_e32 v136, v136, v137
	v_cvt_pk_bf16_f32 v136, v136, v139
	v_cvt_pk_bf16_f32 v137, v138, v145
	v_cvt_pk_bf16_f32 v138, v122, v123
	v_mov_b32_e32 v139, v81
	v_cvt_pk_bf16_f32 v138, v124, v125
	v_cvt_pk_bf16_f32 v126, v126, v127
	v_mov_b32_e32 v152, v91
	v_cvt_pk_bf16_f32 v126, v128, v129
	v_cndmask_b32_e64 v128, v110, v130, s[8:9]
	v_cndmask_b32_e64 v126, v110, v130, s[6:7]
	v_cndmask_b32_e64 v130, v113, v133, s[6:7]
	v_cndmask_b32_e64 v133, v113, v133, s[8:9]
	v_mov_b32_dpp v127, v126 row_ror:1 row_mask:0xf bank_mask:0xf
	v_mov_b32_dpp v140, v128 row_ror:2 row_mask:0xf bank_mask:0xf
	v_cndmask_b32_e64 v126, v111, v131, s[6:7]
	v_cndmask_b32_e64 v128, v111, v131, s[8:9]
	v_mov_b32_dpp v131, v130 row_ror:1 row_mask:0xf bank_mask:0xf
	v_mov_b32_dpp v133, v133 row_ror:2 row_mask:0xf bank_mask:0xf
	v_mov_b32_e32 v138, v113
	v_mov_b32_e32 v130, v77
	v_mov_b32_dpp v129, v126 row_ror:1 row_mask:0xf bank_mask:0xf
	s_waitcnt lgkmcnt(2)
	v_pk_mul_f32 v[130:131], v[138:139], v[130:131]
	s_waitcnt lgkmcnt(1)
	v_fma_f32 v133, v69, v133, v73
	v_add_f32_e32 v131, v131, v133
	v_add_f32_e32 v138, v130, v131
	v_mul_f32_e32 v130, 0xbfb8aa3b, v138
	v_mov_b32_dpp v126, v128 row_ror:2 row_mask:0xf bank_mask:0xf
	v_cndmask_b32_e64 v128, v112, v132, s[6:7]
	v_exp_f32_e32 v130, v130
	v_cndmask_b32_e64 v132, v112, v132, s[8:9]
	v_mov_b32_dpp v131, v128 row_ror:1 row_mask:0xf bank_mask:0xf
	s_nop 1
	v_mov_b32_dpp v128, v132 row_ror:2 row_mask:0xf bank_mask:0xf
	v_add_f32_e32 v130, 1.0, v130
	v_rcp_f32_e32 v139, v130
	v_mov_b32_e32 v132, v112
	v_mov_b32_e32 v133, v80
	v_mov_b32_e32 v130, v76
	s_waitcnt lgkmcnt(1)
	v_pk_mul_f32 v[130:131], v[132:133], v[130:131]
	s_waitcnt lgkmcnt(0)
	v_fma_f32 v128, v68, v128, v72
	v_add_f32_e32 v128, v131, v128
	v_add_f32_e32 v128, v130, v128
	v_mul_f32_e32 v130, 0xbfb8aa3b, v128
	v_exp_f32_e32 v130, v130
	v_mul_f32_e32 v131, v121, v138
	v_mul_f32_e32 v133, v120, v128
	v_mul_f32_e32 v132, v131, v139
	v_add_f32_e32 v128, 1.0, v130
	v_rcp_f32_e32 v138, v128
	v_mov_b32_e32 v130, v111
	v_mov_b32_e32 v131, v79
	v_mov_b32_e32 v128, v75
	v_pk_mul_f32 v[128:129], v[130:131], v[128:129]
	v_fma_f32 v126, v67, v126, v71
	v_add_f32_e32 v126, v129, v126
	v_add_f32_e32 v130, v128, v126
	v_mul_f32_e32 v126, 0xbfb8aa3b, v130
	v_exp_f32_e32 v131, v126
	v_mov_b32_e32 v128, v110
	v_mov_b32_e32 v129, v78
	v_mov_b32_e32 v126, v74
	v_pk_mul_f32 v[126:127], v[128:129], v[126:127]
	v_fma_f32 v128, v66, v140, v70
	v_add_f32_e32 v127, v127, v128
	v_add_f32_e32 v126, v126, v127
	v_mul_f32_e32 v127, 0xbfb8aa3b, v126
	v_exp_f32_e32 v127, v127
	v_add_f32_e32 v129, 1.0, v131
	v_rcp_f32_e32 v129, v129
	v_mul_f32_e32 v126, v118, v126
	v_add_f32_e32 v127, 1.0, v127
	v_rcp_f32_e32 v127, v127
	v_mul_f32_e32 v130, v119, v130
	v_mul_f32_e32 v128, v133, v138
	v_mul_f32_e32 v129, v130, v129
	v_mul_f32_e32 v126, v126, v127
	v_cvt_pk_bf16_f32 v138, v126, v129
	v_cvt_pk_bf16_f32 v139, v128, v132
	v_cvt_pk_bf16_f32 v126, v110, v111
	v_mov_b32_e32 v127, v97
	v_cvt_pk_bf16_f32 v126, v112, v113
	v_cvt_pk_bf16_f32 v118, v118, v119
	v_mov_b32_e32 v142, v77
	v_cvt_pk_bf16_f32 v118, v120, v121
	v_cndmask_b32_e64 v120, v114, v122, s[8:9]
	v_or_b32_e32 v118, 32, v156
	v_mad_i64_i32 v[118:119], s[16:17], v118, s78, v[134:135]
	v_lshl_add_u64 v[118:119], v[118:119], 0, v[154:155]
	global_store_dwordx4 v[118:119], v[136:139], off
	v_cndmask_b32_e64 v118, v114, v122, s[6:7]
	v_cndmask_b32_e64 v122, v117, v125, s[6:7]
	v_cndmask_b32_e64 v125, v117, v125, s[8:9]
	v_mov_b32_dpp v119, v118 row_ror:1 row_mask:0xf bank_mask:0xf
	v_mov_b32_dpp v128, v120 row_ror:2 row_mask:0xf bank_mask:0xf
	v_cndmask_b32_e64 v118, v115, v123, s[6:7]
	v_cndmask_b32_e64 v120, v115, v123, s[8:9]
	v_mov_b32_dpp v123, v122 row_ror:1 row_mask:0xf bank_mask:0xf
	v_mov_b32_dpp v125, v125 row_ror:2 row_mask:0xf bank_mask:0xf
	v_mov_b32_e32 v126, v117
	v_mov_b32_e32 v122, v93
	v_mov_b32_dpp v121, v118 row_ror:1 row_mask:0xf bank_mask:0xf
	s_waitcnt lgkmcnt(2)
; __device__ __forceinline__ unsigned cvt_pk_bf16(float lo, float hi) { unsigned r; asm volatile("v_cvt_pk_bf16_f32 %0, %1, %2" : "=v"(r) : "v"(lo), "v"(hi)); return r; }
;     __device__ __forceinline__ void operator()(const f32x4 (&acc)[2][2][4][2], const Unit& u, int wr, int wc, int fr, int fq) const {
;     ...
;                     const f32x4 g = acc[ai][0][m][n], uu = acc[ai][1][m][n], gp = acc[ai][0][m > 0 ? m - 1 : 0][n];
;                     f32x4 r;
; #pragma unroll
;                     for (int e = 0; e < 4; ++e) {
;                         const float s1 = (fr == 15) ? gp[e] : g[e], s2 = (fr >= 14) ? gp[e] : g[e];
;                         const float p1 = __int_as_float(__builtin_amdgcn_ds_bpermute(src1, __float_as_int(s1))), p2 = __int_as_float(__builtin_amdgcn_ds_bpermute(src2, __float_as_int(s2)));
;                         const float c = bb[n][e] + w0[n][e] * p2 + w1[n][e] * p1 + w2[n][e] * g[e];
;                         r[e] = c * uu[e] * __builtin_amdgcn_rcpf(1.0f + __builtin_amdgcn_exp2f(c * -1.4426950408889634f));
;                     }
;                     if (n == 0) { wa.x = cvt_pk_bf16(r[0], r[1]); wa.y = cvt_pk_bf16(r[2], r[3]); wg.x = cvt_pk_bf16(g[0], g[1]); wg.y = cvt_pk_bf16(g[2], g[3]); wu.x = cvt_pk_bf16(uu[0], uu[1]); wu.y = cvt_pk_bf16(uu[2], uu[3]); }
;                     else { wa.z = cvt_pk_bf16(r[0], r[1]); wa.w = cvt_pk_bf16(r[2], r[3]); wg.z = cvt_pk_bf16(g[0], g[1]); wg.w = cvt_pk_bf16(g[2], g[3]); wu.z = cvt_pk_bf16(uu[0], uu[1]); wu.w = cvt_pk_bf16(uu[2], uu[3]); }
;                 }
;                 if (m == 0 && fr < 2) {
;                     *(u32x4*)(hg + (size_t)(blk * 4 + 2 + fr) * dff + f0) = wg; *(u32x4*)(hu + (size_t)(blk * 2 + fr) * dff + f0) = wu;
;                 } else {
;                     *(u32x4*)(act + (size_t)(rowb + m * 16 + fr) * dff + f0) = wa;
;                 }
;                 if (m == 3 && fr >= 14) *(u32x4*)(hg + (size_t)(blk * 4 + fr - 14) * dff + f0) = wg;
	v_pk_mul_f32 v[122:123], v[126:127], v[122:123]
	s_waitcnt lgkmcnt(1)
	v_fma_f32 v125, v89, v125, v105
	v_add_f32_e32 v123, v123, v125
	v_add_f32_e32 v126, v122, v123
	v_mul_f32_e32 v122, 0xbfb8aa3b, v126
	v_mov_b32_dpp v118, v120 row_ror:2 row_mask:0xf bank_mask:0xf
	v_cndmask_b32_e64 v120, v116, v124, s[6:7]
	v_exp_f32_e32 v122, v122
	v_cndmask_b32_e64 v124, v116, v124, s[8:9]
	v_mov_b32_dpp v123, v120 row_ror:1 row_mask:0xf bank_mask:0xf
	s_nop 1
	v_mov_b32_dpp v120, v124 row_ror:2 row_mask:0xf bank_mask:0xf
	v_add_f32_e32 v122, 1.0, v122
	v_rcp_f32_e32 v127, v122
	v_mov_b32_e32 v124, v116
	v_mov_b32_e32 v125, v96
	v_mov_b32_e32 v122, v92
	s_waitcnt lgkmcnt(1)
	v_pk_mul_f32 v[122:123], v[124:125], v[122:123]
	s_waitcnt lgkmcnt(0)
	v_fma_f32 v120, v88, v120, v104
	v_add_f32_e32 v120, v123, v120
	v_add_f32_e32 v120, v122, v120
	v_mul_f32_e32 v122, 0xbfb8aa3b, v120
	v_exp_f32_e32 v122, v122
	v_mul_f32_e32 v123, v109, v126
	v_mul_f32_e32 v125, v108, v120
	v_mul_f32_e32 v124, v123, v127
	v_add_f32_e32 v120, 1.0, v122
	v_rcp_f32_e32 v126, v120
	v_mov_b32_e32 v122, v115
	v_mov_b32_e32 v123, v95
	v_mov_b32_e32 v120, v91
	v_pk_mul_f32 v[120:121], v[122:123], v[120:121]
	v_fma_f32 v118, v87, v118, v103
	v_add_f32_e32 v118, v121, v118
	v_add_f32_e32 v122, v120, v118
	v_mul_f32_e32 v118, 0xbfb8aa3b, v122
	v_exp_f32_e32 v123, v118
	v_mov_b32_e32 v120, v114
	v_mov_b32_e32 v121, v94
	v_mov_b32_e32 v118, v90
	v_pk_mul_f32 v[118:119], v[120:121], v[118:119]
	v_fma_f32 v120, v86, v128, v102
	v_add_f32_e32 v119, v119, v120
	v_add_f32_e32 v118, v118, v119
	v_mul_f32_e32 v119, 0xbfb8aa3b, v118
	v_exp_f32_e32 v119, v119
	v_add_f32_e32 v121, 1.0, v123
	v_rcp_f32_e32 v121, v121
	v_mul_f32_e32 v118, v106, v118
	v_add_f32_e32 v119, 1.0, v119
	v_rcp_f32_e32 v119, v119
	v_mul_f32_e32 v122, v107, v122
	v_mul_f32_e32 v120, v125, v126
	v_mul_f32_e32 v121, v122, v121
	v_mul_f32_e32 v118, v118, v119
	v_cvt_pk_bf16_f32 v118, v118, v121
	v_cvt_pk_bf16_f32 v119, v120, v124
	v_cvt_pk_bf16_f32 v114, v114, v115
	v_cvt_pk_bf16_f32 v115, v116, v117
	v_cvt_pk_bf16_f32 v106, v106, v107
	v_mov_b32_e32 v116, v101
	v_cvt_pk_bf16_f32 v106, v108, v109
	v_cndmask_b32_e64 v108, v98, v110, s[8:9]
	v_cndmask_b32_e64 v106, v98, v110, s[6:7]
	v_cndmask_b32_e64 v110, v101, v113, s[6:7]
	v_cndmask_b32_e64 v113, v101, v113, s[8:9]
	v_mov_b32_dpp v107, v106 row_ror:1 row_mask:0xf bank_mask:0xf
	v_mov_b32_dpp v120, v108 row_ror:2 row_mask:0xf bank_mask:0xf
	v_cndmask_b32_e64 v106, v99, v111, s[6:7]
	v_cndmask_b32_e64 v108, v99, v111, s[8:9]
	v_mov_b32_dpp v111, v110 row_ror:1 row_mask:0xf bank_mask:0xf
	v_mov_b32_dpp v113, v113 row_ror:2 row_mask:0xf bank_mask:0xf
	v_mov_b32_e32 v117, v81
	v_mov_b32_e32 v110, v77
	v_mov_b32_dpp v109, v106 row_ror:1 row_mask:0xf bank_mask:0xf
	s_waitcnt lgkmcnt(2)
	v_pk_mul_f32 v[110:111], v[116:117], v[110:111]
	s_waitcnt lgkmcnt(1)
	v_fma_f32 v113, v69, v113, v73
	v_add_f32_e32 v111, v111, v113
	v_add_f32_e32 v116, v110, v111
	v_mul_f32_e32 v110, 0xbfb8aa3b, v116
	v_mov_b32_dpp v106, v108 row_ror:2 row_mask:0xf bank_mask:0xf
	v_cndmask_b32_e64 v108, v100, v112, s[6:7]
	v_exp_f32_e32 v110, v110
	v_cndmask_b32_e64 v112, v100, v112, s[8:9]
	v_mov_b32_dpp v111, v108 row_ror:1 row_mask:0xf bank_mask:0xf
	s_nop 1
	v_mov_b32_dpp v108, v112 row_ror:2 row_mask:0xf bank_mask:0xf
	v_add_f32_e32 v110, 1.0, v110
	v_rcp_f32_e32 v117, v110
	v_mov_b32_e32 v112, v100
	v_mov_b32_e32 v113, v80
	v_mov_b32_e32 v110, v76
	s_waitcnt lgkmcnt(1)
	v_pk_mul_f32 v[110:111], v[112:113], v[110:111]
	s_waitcnt lgkmcnt(0)
	v_fma_f32 v108, v68, v108, v72
	v_add_f32_e32 v108, v111, v108
	v_add_f32_e32 v108, v110, v108
	v_mul_f32_e32 v110, 0xbfb8aa3b, v108
	v_exp_f32_e32 v110, v110
	v_mul_f32_e32 v111, v85, v116
	v_mul_f32_e32 v113, v84, v108
	v_mul_f32_e32 v112, v111, v117
	v_add_f32_e32 v108, 1.0, v110
	v_rcp_f32_e32 v116, v108
	v_mov_b32_e32 v110, v99
	v_mov_b32_e32 v111, v79
	v_mov_b32_e32 v108, v75
	v_pk_mul_f32 v[108:109], v[110:111], v[108:109]
	v_fma_f32 v106, v67, v106, v71
	v_add_f32_e32 v106, v109, v106
	v_add_f32_e32 v110, v108, v106
	v_mul_f32_e32 v106, 0xbfb8aa3b, v110
	v_exp_f32_e32 v111, v106
	v_mov_b32_e32 v108, v98
	v_mov_b32_e32 v109, v78
	v_mov_b32_e32 v106, v74
	v_pk_mul_f32 v[106:107], v[108:109], v[106:107]
	v_fma_f32 v108, v66, v120, v70
	v_add_f32_e32 v107, v107, v108
	v_add_f32_e32 v106, v106, v107
	v_mul_f32_e32 v107, 0xbfb8aa3b, v106
	v_exp_f32_e32 v107, v107
	v_add_f32_e32 v109, 1.0, v111
	v_rcp_f32_e32 v109, v109
	v_mul_f32_e32 v110, v83, v110
	v_add_f32_e32 v107, 1.0, v107
	v_rcp_f32_e32 v107, v107
	v_mul_f32_e32 v106, v82, v106
	v_mul_f32_e32 v108, v113, v116
	v_mul_f32_e32 v109, v110, v109
	v_mul_f32_e32 v106, v106, v107
	v_cvt_pk_bf16_f32 v120, v106, v109
	v_cvt_pk_bf16_f32 v121, v108, v112
	v_cvt_pk_bf16_f32 v116, v98, v99
	v_cvt_pk_bf16_f32 v117, v100, v101
	v_cvt_pk_bf16_f32 v82, v82, v83
	v_mov_b32_e32 v144, v75
	v_cvt_pk_bf16_f32 v82, v84, v85
	s_nop 0
	v_or_b32_e32 v82, 48, v156
	v_mad_i64_i32 v[82:83], s[16:17], v82, s78, v[134:135]
	v_lshl_add_u64 v[82:83], v[82:83], 0, v[154:155]
	global_store_dwordx4 v[82:83], v[118:121], off
	s_and_saveexec_b64 s[56:57], s[8:9]
	s_cbranch_execz .LBB0_488
	v_add_u32_e32 v84, s47, v214
	v_mov_b64_e32 v[82:83], s[28:29]
	v_mad_i64_i32 v[82:83], s[16:17], v84, s78, v[82:83]
	v_lshl_add_u64 v[82:83], v[196:197], 1, v[82:83]
	global_store_dwordx4 v[82:83], v[114:117], off
; __device__ __forceinline__ unsigned cvt_pk_bf16(float lo, float hi) { unsigned r; asm volatile("v_cvt_pk_bf16_f32 %0, %1, %2" : "=v"(r) : "v"(lo), "v"(hi)); return r; }
;     __device__ __forceinline__ void operator()(const f32x4 (&acc)[2][2][4][2], const Unit& u, int wr, int wc, int fr, int fq) const {
;     ...
;                     const f32x4 g = acc[ai][0][m][n], uu = acc[ai][1][m][n], gp = acc[ai][0][m > 0 ? m - 1 : 0][n];
;                     f32x4 r;
; #pragma unroll
;                     for (int e = 0; e < 4; ++e) {
;                         const float s1 = (fr == 15) ? gp[e] : g[e], s2 = (fr >= 14) ? gp[e] : g[e];
;                         const float p1 = __int_as_float(__builtin_amdgcn_ds_bpermute(src1, __float_as_int(s1))), p2 = __int_as_float(__builtin_amdgcn_ds_bpermute(src2, __float_as_int(s2)));
;                         const float c = bb[n][e] + w0[n][e] * p2 + w1[n][e] * p1 + w2[n][e] * g[e];
;                         r[e] = c * uu[e] * __builtin_amdgcn_rcpf(1.0f + __builtin_amdgcn_exp2f(c * -1.4426950408889634f));
;                     }
;                     if (n == 0) { wa.x = cvt_pk_bf16(r[0], r[1]); wa.y = cvt_pk_bf16(r[2], r[3]); wg.x = cvt_pk_bf16(g[0], g[1]); wg.y = cvt_pk_bf16(g[2], g[3]); wu.x = cvt_pk_bf16(uu[0], uu[1]); wu.y = cvt_pk_bf16(uu[2], uu[3]); }
;                     else { wa.z = cvt_pk_bf16(r[0], r[1]); wa.w = cvt_pk_bf16(r[2], r[3]); wg.z = cvt_pk_bf16(g[0], g[1]); wg.w = cvt_pk_bf16(g[2], g[3]); wu.z = cvt_pk_bf16(uu[0], uu[1]); wu.w = cvt_pk_bf16(uu[2], uu[3]); }
;                 }
;                 if (m == 0 && fr < 2) {
;                     *(u32x4*)(hg + (size_t)(blk * 4 + 2 + fr) * dff + f0) = wg; *(u32x4*)(hu + (size_t)(blk * 2 + fr) * dff + f0) = wu;
;                 } else {
;                     *(u32x4*)(act + (size_t)(rowb + m * 16 + fr) * dff + f0) = wa;
;                 }
;                 if (m == 3 && fr >= 14) *(u32x4*)(hg + (size_t)(blk * 4 + fr - 14) * dff + f0) = wg;
.LBB0_488:
	s_or_b64 exec, exec, s[56:57]
	v_mov_b32_dpp v82, v57 row_ror:2 row_mask:0xf bank_mask:0xf
	v_mov_b32_dpp v83, v57 row_ror:1 row_mask:0xf bank_mask:0xf
	v_mov_b32_dpp v99, v56 row_ror:1 row_mask:0xf bank_mask:0xf
	v_mov_b32_dpp v100, v55 row_ror:2 row_mask:0xf bank_mask:0xf
	v_mov_b32_dpp v85, v54 row_ror:2 row_mask:0xf bank_mask:0xf
	s_waitcnt lgkmcnt(4)
	v_fma_f32 v82, v89, v82, v105
	s_waitcnt lgkmcnt(3)
	v_fmac_f32_e32 v82, v97, v83
	v_fmac_f32_e32 v82, v57, v93
	v_mov_b32_dpp v93, v56 row_ror:2 row_mask:0xf bank_mask:0xf
	v_mul_f32_e32 v83, 0xbfb8aa3b, v82
	v_exp_f32_e32 v83, v83
	v_mov_b32_dpp v98, v55 row_ror:1 row_mask:0xf bank_mask:0xf
	v_mov_b32_dpp v84, v54 row_ror:1 row_mask:0xf bank_mask:0xf
	s_waitcnt lgkmcnt(2)
	v_fma_f32 v93, v88, v93, v104
	v_fmac_f32_e32 v93, v96, v99
	v_fmac_f32_e32 v93, v56, v92
	v_add_f32_e32 v83, 1.0, v83
	v_mul_f32_e32 v99, 0xbfb8aa3b, v93
	v_rcp_f32_e32 v83, v83
	v_exp_f32_e32 v99, v99
	v_mul_f32_e32 v82, v65, v82
	v_fma_f32 v85, v86, v85, v102
	v_mul_f32_e32 v83, v82, v83
	v_mul_f32_e32 v82, v64, v93
	v_add_f32_e32 v93, 1.0, v99
	v_fma_f32 v99, v87, v100, v103
	s_waitcnt lgkmcnt(1)
	v_fmac_f32_e32 v99, v95, v98
	v_fmac_f32_e32 v99, v55, v91
	s_waitcnt lgkmcnt(0)
	v_fmac_f32_e32 v85, v94, v84
	v_mul_f32_e32 v91, 0xbfb8aa3b, v99
	v_fmac_f32_e32 v85, v54, v90
	v_rcp_f32_e32 v93, v93
	v_exp_f32_e32 v91, v91
	v_mul_f32_e32 v84, 0xbfb8aa3b, v85
	v_exp_f32_e32 v84, v84
	v_mul_f32_e32 v93, v82, v93
	v_add_f32_e32 v82, 1.0, v91
	v_rcp_f32_e32 v82, v82
	v_add_f32_e32 v84, 1.0, v84
	v_rcp_f32_e32 v84, v84
	v_mul_f32_e32 v91, v63, v99
	v_mul_f32_e32 v82, v91, v82
	v_mul_f32_e32 v85, v62, v85
	v_mul_f32_e32 v84, v85, v84
	v_cvt_pk_bf16_f32 v82, v84, v82
	v_cvt_pk_bf16_f32 v83, v93, v83
	v_cvt_pk_bf16_f32 v98, v54, v55
	v_cvt_pk_bf16_f32 v99, v56, v57
	v_cvt_pk_bf16_f32 v62, v62, v63
	v_cvt_pk_bf16_f32 v63, v64, v65
	v_mov_b32_dpp v64, v53 row_ror:2 row_mask:0xf bank_mask:0xf
	v_mov_b32_dpp v65, v53 row_ror:1 row_mask:0xf bank_mask:0xf
	v_mov_b32_dpp v93, v52 row_ror:1 row_mask:0xf bank_mask:0xf
	v_mov_b32_dpp v100, v51 row_ror:2 row_mask:0xf bank_mask:0xf
	v_mov_b32_dpp v85, v50 row_ror:2 row_mask:0xf bank_mask:0xf
	s_waitcnt lgkmcnt(4)
	v_fma_f32 v64, v69, v64, v73
	s_waitcnt lgkmcnt(3)
	v_fmac_f32_e32 v64, v81, v65
	v_fmac_f32_e32 v64, v53, v77
	v_mov_b32_dpp v77, v52 row_ror:2 row_mask:0xf bank_mask:0xf
	v_mul_f32_e32 v65, 0xbfb8aa3b, v64
	v_exp_f32_e32 v65, v65
	v_mov_b32_dpp v91, v51 row_ror:1 row_mask:0xf bank_mask:0xf
	v_mov_b32_dpp v84, v50 row_ror:1 row_mask:0xf bank_mask:0xf
	s_waitcnt lgkmcnt(2)
	v_fma_f32 v77, v68, v77, v72
	v_fmac_f32_e32 v77, v80, v93
	v_fmac_f32_e32 v77, v52, v76
	v_add_f32_e32 v65, 1.0, v65
	v_mul_f32_e32 v93, 0xbfb8aa3b, v77
	v_rcp_f32_e32 v65, v65
	v_exp_f32_e32 v93, v93
	v_mul_f32_e32 v64, v61, v64
	v_fma_f32 v85, v66, v85, v70
	v_mul_f32_e32 v64, v64, v65
	v_mul_f32_e32 v65, v60, v77
	v_add_f32_e32 v77, 1.0, v93
	v_fma_f32 v93, v67, v100, v71
	s_waitcnt lgkmcnt(1)
	v_fmac_f32_e32 v93, v79, v91
	v_fmac_f32_e32 v93, v51, v75
	s_waitcnt lgkmcnt(0)
	v_fmac_f32_e32 v85, v78, v84
	v_mul_f32_e32 v75, 0xbfb8aa3b, v93
	v_fmac_f32_e32 v85, v50, v74
	v_exp_f32_e32 v75, v75
	v_mul_f32_e32 v84, 0xbfb8aa3b, v85
	v_rcp_f32_e32 v77, v77
	v_exp_f32_e32 v84, v84
	v_add_f32_e32 v75, 1.0, v75
	v_rcp_f32_e32 v75, v75
	v_mul_f32_e32 v65, v65, v77
	v_add_f32_e32 v77, 1.0, v84
	v_rcp_f32_e32 v77, v77
	v_mul_f32_e32 v84, v59, v93
	v_mul_f32_e32 v75, v84, v75
	v_mul_f32_e32 v84, v58, v85
	v_mul_f32_e32 v77, v84, v77
	v_cvt_pk_bf16_f32 v84, v77, v75
	v_cvt_pk_bf16_f32 v85, v65, v64
	v_cvt_pk_bf16_f32 v100, v50, v51
	v_cvt_pk_bf16_f32 v101, v52, v53
	v_cvt_pk_bf16_f32 v64, v58, v59
	v_cvt_pk_bf16_f32 v65, v60, v61
	s_and_saveexec_b64 s[16:17], s[10:11]
	s_xor_b64 s[56:57], exec, s[16:17]
	s_or_saveexec_b64 s[56:57], s[56:57]
	s_add_i32 s47, s45, 0x80
	v_or_b32_e32 v60, s47, v170
	s_ashr_i32 s45, s47, 4
	v_mov_b64_e32 v[58:59], s[22:23]
	v_mov_b32_e32 v61, v60
	s_xor_b64 exec, exec, s[56:57]
	s_cbranch_execz .LBB0_492
	s_ashr_i32 s16, s47, 5
	v_or_b32_e32 v75, s45, v215
	v_mov_b64_e32 v[58:59], s[28:29]
	v_or_b32_e32 v61, s16, v170
	v_mad_i64_i32 v[58:59], s[16:17], v75, s78, v[58:59]
	v_lshl_add_u64 v[58:59], v[196:197], 1, v[58:59]
	v_mov_b64_e32 v[84:85], v[64:65]
	global_store_dwordx4 v[58:59], v[98:101], off
	v_mov_b64_e32 v[58:59], s[30:31]
	v_mov_b64_e32 v[82:83], v[62:63]
; __device__ __forceinline__ unsigned cvt_pk_bf16(float lo, float hi) { unsigned r; asm volatile("v_cvt_pk_bf16_f32 %0, %1, %2" : "=v"(r) : "v"(lo), "v"(hi)); return r; }
;     __device__ __forceinline__ void operator()(const f32x4 (&acc)[2][2][4][2], const Unit& u, int wr, int wc, int fr, int fq) const {
;     ...
;                     const f32x4 g = acc[ai][0][m][n], uu = acc[ai][1][m][n], gp = acc[ai][0][m > 0 ? m - 1 : 0][n];
;                     f32x4 r;
; #pragma unroll
;                     for (int e = 0; e < 4; ++e) {
;                         const float s1 = (fr == 15) ? gp[e] : g[e], s2 = (fr >= 14) ? gp[e] : g[e];
;                         const float p1 = __int_as_float(__builtin_amdgcn_ds_bpermute(src1, __float_as_int(s1))), p2 = __int_as_float(__builtin_amdgcn_ds_bpermute(src2, __float_as_int(s2)));
;                         const float c = bb[n][e] + w0[n][e] * p2 + w1[n][e] * p1 + w2[n][e] * g[e];
;                         r[e] = c * uu[e] * __builtin_amdgcn_rcpf(1.0f + __builtin_amdgcn_exp2f(c * -1.4426950408889634f));
;                     }
;                     if (n == 0) { wa.x = cvt_pk_bf16(r[0], r[1]); wa.y = cvt_pk_bf16(r[2], r[3]); wg.x = cvt_pk_bf16(g[0], g[1]); wg.y = cvt_pk_bf16(g[2], g[3]); wu.x = cvt_pk_bf16(uu[0], uu[1]); wu.y = cvt_pk_bf16(uu[2], uu[3]); }
;                     else { wa.z = cvt_pk_bf16(r[0], r[1]); wa.w = cvt_pk_bf16(r[2], r[3]); wg.z = cvt_pk_bf16(g[0], g[1]); wg.w = cvt_pk_bf16(g[2], g[3]); wu.z = cvt_pk_bf16(uu[0], uu[1]); wu.w = cvt_pk_bf16(uu[2], uu[3]); }
;                 }
;                 if (m == 0 && fr < 2) {
;                     *(u32x4*)(hg + (size_t)(blk * 4 + 2 + fr) * dff + f0) = wg; *(u32x4*)(hu + (size_t)(blk * 2 + fr) * dff + f0) = wu;
;                 } else {
;                     *(u32x4*)(act + (size_t)(rowb + m * 16 + fr) * dff + f0) = wa;
;                 }
;                 if (m == 3 && fr >= 14) *(u32x4*)(hg + (size_t)(blk * 4 + fr - 14) * dff + f0) = wg;
.LBB0_492:
	s_or_b64 exec, exec, s[56:57]
	v_mad_i64_i32 v[58:59], s[16:17], v61, s78, v[58:59]
	v_lshl_add_u64 v[58:59], v[58:59], 0, v[154:155]
	global_store_dwordx4 v[58:59], v[82:85], off
	v_cndmask_b32_e64 v58, v42, v54, s[6:7]
	v_cndmask_b32_e64 v54, v42, v54, s[8:9]
	s_nop 1
	v_mov_b32_dpp v91, v58 row_ror:1 row_mask:0xf bank_mask:0xf
	v_mov_b32_dpp v58, v54 row_ror:2 row_mask:0xf bank_mask:0xf
	v_cndmask_b32_e64 v54, v43, v55, s[6:7]
	v_cndmask_b32_e64 v55, v43, v55, s[8:9]
	s_nop 1
	v_mov_b32_dpp v153, v54 row_ror:1 row_mask:0xf bank_mask:0xf
	v_mov_b32_dpp v59, v55 row_ror:2 row_mask:0xf bank_mask:0xf
	v_cndmask_b32_e64 v54, v45, v57, s[6:7]
	v_cndmask_b32_e64 v55, v45, v57, s[8:9]
	s_nop 1
	v_mov_b32_dpp v151, v54 row_ror:1 row_mask:0xf bank_mask:0xf
	v_mov_b32_dpp v57, v55 row_ror:2 row_mask:0xf bank_mask:0xf
	v_mov_b32_e32 v54, v45
	v_mov_b32_e32 v55, v97
	v_cndmask_b32_e64 v61, v44, v56, s[6:7]
	s_waitcnt lgkmcnt(1)
	v_pk_mul_f32 v[54:55], v[54:55], v[150:151]
	s_waitcnt lgkmcnt(0)
	v_fma_f32 v57, v89, v57, v105
	v_add_f32_e32 v55, v55, v57
	v_add_f32_e32 v57, v54, v55
	v_mul_f32_e32 v54, 0xbfb8aa3b, v57
	v_exp_f32_e32 v54, v54
	v_cndmask_b32_e64 v55, v44, v56, s[8:9]
	v_mov_b32_dpp v93, v61 row_ror:1 row_mask:0xf bank_mask:0xf
	s_nop 1
	v_mov_b32_dpp v56, v55 row_ror:2 row_mask:0xf bank_mask:0xf
	v_add_f32_e32 v54, 1.0, v54
	v_rcp_f32_e32 v61, v54
	v_mov_b32_e32 v54, v44
	v_mov_b32_e32 v55, v96
	s_waitcnt lgkmcnt(1)
	v_pk_mul_f32 v[54:55], v[54:55], v[92:93]
	s_waitcnt lgkmcnt(0)
	v_fma_f32 v56, v88, v56, v104
	v_add_f32_e32 v55, v55, v56
	v_add_f32_e32 v54, v54, v55
	v_mul_f32_e32 v55, 0xbfb8aa3b, v54
	v_exp_f32_e32 v55, v55
	v_mul_f32_e32 v56, v49, v57
	v_mul_f32_e32 v57, v48, v54
	v_mul_f32_e32 v56, v56, v61
	v_add_f32_e32 v54, 1.0, v55
	v_rcp_f32_e32 v61, v54
	v_mov_b32_e32 v54, v43
	v_mov_b32_e32 v55, v95
	v_pk_mul_f32 v[54:55], v[54:55], v[152:153]
	v_fma_f32 v59, v87, v59, v103
	v_add_f32_e32 v55, v55, v59
	v_add_f32_e32 v59, v54, v55
	v_mul_f32_e32 v54, 0xbfb8aa3b, v59
	v_exp_f32_e32 v62, v54
	v_mov_b32_e32 v54, v42
	v_mov_b32_e32 v55, v94
	v_pk_mul_f32 v[54:55], v[54:55], v[90:91]
	v_fma_f32 v58, v86, v58, v102
	v_add_f32_e32 v55, v55, v58
	v_add_f32_e32 v54, v54, v55
	v_mul_f32_e32 v55, 0xbfb8aa3b, v54
	v_exp_f32_e32 v55, v55
	v_add_f32_e32 v58, 1.0, v62
	v_rcp_f32_e32 v58, v58
	v_mul_f32_e32 v54, v46, v54
	v_add_f32_e32 v55, 1.0, v55
	v_rcp_f32_e32 v55, v55
	v_mul_f32_e32 v59, v47, v59
	v_mul_f32_e32 v57, v57, v61
	v_mul_f32_e32 v58, v59, v58
	v_mul_f32_e32 v54, v54, v55
	v_cvt_pk_bf16_f32 v54, v54, v58
	v_cvt_pk_bf16_f32 v55, v57, v56
	v_cvt_pk_bf16_f32 v56, v42, v43
	s_nop 0
	v_cvt_pk_bf16_f32 v56, v44, v45
	v_cvt_pk_bf16_f32 v46, v46, v47
	v_cndmask_b32_e64 v47, v34, v50, s[8:9]
	v_cvt_pk_bf16_f32 v46, v48, v49
	s_nop 1
	v_mov_b32_dpp v48, v47 row_ror:2 row_mask:0xf bank_mask:0xf
	v_cndmask_b32_e64 v46, v34, v50, s[6:7]
	s_nop 1
	v_mov_b32_dpp v75, v46 row_ror:1 row_mask:0xf bank_mask:0xf
	v_cndmask_b32_e64 v46, v35, v51, s[6:7]
	v_cndmask_b32_e64 v47, v35, v51, s[8:9]
	s_nop 1
	v_mov_b32_dpp v145, v46 row_ror:1 row_mask:0xf bank_mask:0xf
	v_mov_b32_dpp v49, v47 row_ror:2 row_mask:0xf bank_mask:0xf
	v_cndmask_b32_e64 v46, v37, v53, s[6:7]
	v_cndmask_b32_e64 v47, v37, v53, s[8:9]
	s_nop 1
	v_mov_b32_dpp v143, v46 row_ror:1 row_mask:0xf bank_mask:0xf
	v_mov_b32_dpp v50, v47 row_ror:2 row_mask:0xf bank_mask:0xf
	v_mov_b32_e32 v46, v37
	v_mov_b32_e32 v47, v81
	v_cndmask_b32_e64 v51, v36, v52, s[6:7]
	s_waitcnt lgkmcnt(1)
	v_pk_mul_f32 v[46:47], v[46:47], v[142:143]
	s_waitcnt lgkmcnt(0)
	v_fma_f32 v50, v69, v50, v73
	v_add_f32_e32 v47, v47, v50
	v_add_f32_e32 v50, v46, v47
	v_mul_f32_e32 v46, 0xbfb8aa3b, v50
	v_exp_f32_e32 v46, v46
	v_cndmask_b32_e64 v47, v36, v52, s[8:9]
	v_mov_b32_dpp v77, v51 row_ror:1 row_mask:0xf bank_mask:0xf
	s_nop 1
	v_mov_b32_dpp v51, v47 row_ror:2 row_mask:0xf bank_mask:0xf
	v_add_f32_e32 v46, 1.0, v46
	v_rcp_f32_e32 v52, v46
	v_mov_b32_e32 v46, v36
	v_mov_b32_e32 v47, v80
	s_waitcnt lgkmcnt(1)
	v_pk_mul_f32 v[46:47], v[46:47], v[76:77]
	s_waitcnt lgkmcnt(0)
	v_fma_f32 v51, v68, v51, v72
	v_add_f32_e32 v47, v47, v51
	v_add_f32_e32 v46, v46, v47
	v_mul_f32_e32 v47, 0xbfb8aa3b, v46
	v_exp_f32_e32 v47, v47
	v_mul_f32_e32 v50, v41, v50
	v_mul_f32_e32 v51, v40, v46
	v_mul_f32_e32 v50, v50, v52
	v_add_f32_e32 v46, 1.0, v47
	v_rcp_f32_e32 v52, v46
	v_mov_b32_e32 v46, v35
	v_mov_b32_e32 v47, v79
	v_pk_mul_f32 v[46:47], v[46:47], v[144:145]
	v_fma_f32 v49, v67, v49, v71
	v_add_f32_e32 v47, v47, v49
	v_add_f32_e32 v49, v46, v47
	v_mul_f32_e32 v46, 0xbfb8aa3b, v49
	v_exp_f32_e32 v53, v46
	v_mov_b32_e32 v46, v34
	v_mov_b32_e32 v47, v78
	v_pk_mul_f32 v[46:47], v[46:47], v[74:75]
	v_fma_f32 v48, v66, v48, v70
	v_add_f32_e32 v47, v47, v48
	v_add_f32_e32 v46, v46, v47
	v_mul_f32_e32 v47, 0xbfb8aa3b, v46
	v_exp_f32_e32 v47, v47
	v_mul_f32_e32 v48, v51, v52
	v_add_f32_e32 v51, 1.0, v53
	v_rcp_f32_e32 v51, v51
	v_add_f32_e32 v47, 1.0, v47
	v_rcp_f32_e32 v47, v47
	v_mul_f32_e32 v46, v38, v46
	v_mul_f32_e32 v49, v39, v49
	v_mul_f32_e32 v49, v49, v51
	v_mul_f32_e32 v46, v46, v47
	v_cvt_pk_bf16_f32 v56, v46, v49
	v_cvt_pk_bf16_f32 v57, v48, v50
	v_cvt_pk_bf16_f32 v46, v34, v35
	s_nop 0
	v_cvt_pk_bf16_f32 v46, v36, v37
	v_cvt_pk_bf16_f32 v38, v38, v39
	s_nop 0
	v_cvt_pk_bf16_f32 v38, v40, v41
	v_or_b32_e32 v40, 16, v60
	v_mov_b64_e32 v[38:39], s[22:23]
	v_mad_i64_i32 v[40:41], s[16:17], v40, s78, v[38:39]
	v_lshl_add_u64 v[40:41], v[40:41], 0, v[154:155]
	global_store_dwordx4 v[40:41], v[54:57], off
	v_cndmask_b32_e64 v40, v24, v42, s[6:7]
	v_cndmask_b32_e64 v41, v24, v42, s[8:9]
	s_nop 1
	v_mov_b32_dpp v91, v40 row_ror:1 row_mask:0xf bank_mask:0xf
	v_mov_b32_dpp v42, v41 row_ror:2 row_mask:0xf bank_mask:0xf
	v_cndmask_b32_e64 v40, v25, v43, s[6:7]
	v_cndmask_b32_e64 v41, v25, v43, s[8:9]
	s_nop 1
	v_mov_b32_dpp v153, v40 row_ror:1 row_mask:0xf bank_mask:0xf
	v_mov_b32_dpp v43, v41 row_ror:2 row_mask:0xf bank_mask:0xf
	v_cndmask_b32_e64 v40, v27, v45, s[6:7]
	v_cndmask_b32_e64 v41, v27, v45, s[8:9]
	s_nop 1
	v_mov_b32_dpp v151, v40 row_ror:1 row_mask:0xf bank_mask:0xf
	v_mov_b32_dpp v45, v41 row_ror:2 row_mask:0xf bank_mask:0xf
	v_mov_b32_e32 v40, v27
	v_mov_b32_e32 v41, v97
	v_cndmask_b32_e64 v46, v26, v44, s[6:7]
	s_waitcnt lgkmcnt(1)
; __device__ __forceinline__ unsigned cvt_pk_bf16(float lo, float hi) { unsigned r; asm volatile("v_cvt_pk_bf16_f32 %0, %1, %2" : "=v"(r) : "v"(lo), "v"(hi)); return r; }
;     __device__ __forceinline__ void operator()(const f32x4 (&acc)[2][2][4][2], const Unit& u, int wr, int wc, int fr, int fq) const {
;     ...
;                     const f32x4 g = acc[ai][0][m][n], uu = acc[ai][1][m][n], gp = acc[ai][0][m > 0 ? m - 1 : 0][n];
;                     f32x4 r;
; #pragma unroll
;                     for (int e = 0; e < 4; ++e) {
;                         const float s1 = (fr == 15) ? gp[e] : g[e], s2 = (fr >= 14) ? gp[e] : g[e];
;                         const float p1 = __int_as_float(__builtin_amdgcn_ds_bpermute(src1, __float_as_int(s1))), p2 = __int_as_float(__builtin_amdgcn_ds_bpermute(src2, __float_as_int(s2)));
;                         const float c = bb[n][e] + w0[n][e] * p2 + w1[n][e] * p1 + w2[n][e] * g[e];
;                         r[e] = c * uu[e] * __builtin_amdgcn_rcpf(1.0f + __builtin_amdgcn_exp2f(c * -1.4426950408889634f));
;                     }
;                     if (n == 0) { wa.x = cvt_pk_bf16(r[0], r[1]); wa.y = cvt_pk_bf16(r[2], r[3]); wg.x = cvt_pk_bf16(g[0], g[1]); wg.y = cvt_pk_bf16(g[2], g[3]); wu.x = cvt_pk_bf16(uu[0], uu[1]); wu.y = cvt_pk_bf16(uu[2], uu[3]); }
;                     else { wa.z = cvt_pk_bf16(r[0], r[1]); wa.w = cvt_pk_bf16(r[2], r[3]); wg.z = cvt_pk_bf16(g[0], g[1]); wg.w = cvt_pk_bf16(g[2], g[3]); wu.z = cvt_pk_bf16(uu[0], uu[1]); wu.w = cvt_pk_bf16(uu[2], uu[3]); }
;                 }
;                 if (m == 0 && fr < 2) {
;                     *(u32x4*)(hg + (size_t)(blk * 4 + 2 + fr) * dff + f0) = wg; *(u32x4*)(hu + (size_t)(blk * 2 + fr) * dff + f0) = wu;
;                 } else {
;                     *(u32x4*)(act + (size_t)(rowb + m * 16 + fr) * dff + f0) = wa;
;                 }
;                 if (m == 3 && fr >= 14) *(u32x4*)(hg + (size_t)(blk * 4 + fr - 14) * dff + f0) = wg;
	v_pk_mul_f32 v[40:41], v[40:41], v[150:151]
	s_waitcnt lgkmcnt(0)
	v_fma_f32 v45, v89, v45, v105
	v_add_f32_e32 v41, v41, v45
	v_add_f32_e32 v45, v40, v41
	v_mul_f32_e32 v40, 0xbfb8aa3b, v45
	v_exp_f32_e32 v40, v40
	v_cndmask_b32_e64 v41, v26, v44, s[8:9]
	v_mov_b32_dpp v93, v46 row_ror:1 row_mask:0xf bank_mask:0xf
	s_nop 1
	v_mov_b32_dpp v44, v41 row_ror:2 row_mask:0xf bank_mask:0xf
	v_add_f32_e32 v40, 1.0, v40
	v_rcp_f32_e32 v46, v40
	v_mov_b32_e32 v40, v26
	v_mov_b32_e32 v41, v96
	s_waitcnt lgkmcnt(1)
	v_pk_mul_f32 v[40:41], v[40:41], v[92:93]
	s_waitcnt lgkmcnt(0)
	v_fma_f32 v44, v88, v44, v104
	v_add_f32_e32 v41, v41, v44
	v_add_f32_e32 v40, v40, v41
	v_mul_f32_e32 v41, 0xbfb8aa3b, v40
	v_exp_f32_e32 v41, v41
	v_mul_f32_e32 v44, v31, v45
	v_mul_f32_e32 v45, v30, v40
	v_mul_f32_e32 v44, v44, v46
	v_add_f32_e32 v40, 1.0, v41
	v_rcp_f32_e32 v46, v40
	v_mov_b32_e32 v40, v25
	v_mov_b32_e32 v41, v95
	v_pk_mul_f32 v[40:41], v[40:41], v[152:153]
	v_fma_f32 v43, v87, v43, v103
	v_add_f32_e32 v41, v41, v43
	v_add_f32_e32 v43, v40, v41
	v_mul_f32_e32 v40, 0xbfb8aa3b, v43
	v_exp_f32_e32 v47, v40
	v_mov_b32_e32 v40, v24
	v_mov_b32_e32 v41, v94
	v_pk_mul_f32 v[40:41], v[40:41], v[90:91]
	v_fma_f32 v42, v86, v42, v102
	v_add_f32_e32 v41, v41, v42
	v_add_f32_e32 v40, v40, v41
	v_mul_f32_e32 v41, 0xbfb8aa3b, v40
	v_exp_f32_e32 v41, v41
	v_mul_f32_e32 v42, v45, v46
	v_add_f32_e32 v45, 1.0, v47
	v_rcp_f32_e32 v45, v45
	v_add_f32_e32 v41, 1.0, v41
	v_rcp_f32_e32 v41, v41
	v_mul_f32_e32 v40, v28, v40
	v_mul_f32_e32 v43, v29, v43
	v_mul_f32_e32 v43, v43, v45
	v_mul_f32_e32 v40, v40, v41
	v_cvt_pk_bf16_f32 v40, v40, v43
	v_cvt_pk_bf16_f32 v41, v42, v44
	v_cvt_pk_bf16_f32 v42, v24, v25
	s_nop 0
	v_cvt_pk_bf16_f32 v42, v26, v27
	v_cvt_pk_bf16_f32 v28, v28, v29
	v_cndmask_b32_e64 v29, v12, v34, s[8:9]
	v_cvt_pk_bf16_f32 v28, v30, v31
	s_nop 1
	v_mov_b32_dpp v30, v29 row_ror:2 row_mask:0xf bank_mask:0xf
	v_cndmask_b32_e64 v28, v12, v34, s[6:7]
	s_nop 1
	v_mov_b32_dpp v75, v28 row_ror:1 row_mask:0xf bank_mask:0xf
	v_cndmask_b32_e64 v28, v13, v35, s[6:7]
	v_cndmask_b32_e64 v29, v13, v35, s[8:9]
	s_nop 1
	v_mov_b32_dpp v145, v28 row_ror:1 row_mask:0xf bank_mask:0xf
	v_mov_b32_dpp v31, v29 row_ror:2 row_mask:0xf bank_mask:0xf
	v_cndmask_b32_e64 v28, v15, v37, s[6:7]
	v_cndmask_b32_e64 v29, v15, v37, s[8:9]
	s_nop 1
	v_mov_b32_dpp v143, v28 row_ror:1 row_mask:0xf bank_mask:0xf
	v_mov_b32_dpp v34, v29 row_ror:2 row_mask:0xf bank_mask:0xf
	v_mov_b32_e32 v28, v15
	v_mov_b32_e32 v29, v81
	v_cndmask_b32_e64 v35, v14, v36, s[6:7]
	s_waitcnt lgkmcnt(1)
	v_pk_mul_f32 v[28:29], v[28:29], v[142:143]
	s_waitcnt lgkmcnt(0)
	v_fma_f32 v34, v69, v34, v73
	v_add_f32_e32 v29, v29, v34
	v_add_f32_e32 v34, v28, v29
	v_mul_f32_e32 v28, 0xbfb8aa3b, v34
	v_exp_f32_e32 v28, v28
	v_cndmask_b32_e64 v29, v14, v36, s[8:9]
	v_mov_b32_dpp v77, v35 row_ror:1 row_mask:0xf bank_mask:0xf
	s_nop 1
	v_mov_b32_dpp v35, v29 row_ror:2 row_mask:0xf bank_mask:0xf
	v_add_f32_e32 v28, 1.0, v28
	v_rcp_f32_e32 v36, v28
	v_mov_b32_e32 v28, v14
	v_mov_b32_e32 v29, v80
	s_waitcnt lgkmcnt(1)
	v_pk_mul_f32 v[28:29], v[28:29], v[76:77]
	s_waitcnt lgkmcnt(0)
	v_fma_f32 v35, v68, v35, v72
	v_add_f32_e32 v29, v29, v35
	v_add_f32_e32 v28, v28, v29
	v_mul_f32_e32 v29, 0xbfb8aa3b, v28
	v_exp_f32_e32 v29, v29
	v_mul_f32_e32 v34, v23, v34
	v_mul_f32_e32 v35, v22, v28
	v_mul_f32_e32 v34, v34, v36
	v_add_f32_e32 v28, 1.0, v29
	v_rcp_f32_e32 v36, v28
	v_mov_b32_e32 v28, v13
	v_mov_b32_e32 v29, v79
	v_pk_mul_f32 v[28:29], v[28:29], v[144:145]
	v_fma_f32 v31, v67, v31, v71
	v_add_f32_e32 v29, v29, v31
	v_add_f32_e32 v31, v28, v29
	v_mul_f32_e32 v28, 0xbfb8aa3b, v31
	v_exp_f32_e32 v37, v28
	v_mov_b32_e32 v28, v12
	v_mov_b32_e32 v29, v78
	v_pk_mul_f32 v[28:29], v[28:29], v[74:75]
	v_fma_f32 v30, v66, v30, v70
	v_add_f32_e32 v29, v29, v30
	v_add_f32_e32 v28, v28, v29
	v_mul_f32_e32 v29, 0xbfb8aa3b, v28
	v_exp_f32_e32 v29, v29
	v_mul_f32_e32 v30, v35, v36
	v_add_f32_e32 v35, 1.0, v37
	v_rcp_f32_e32 v35, v35
	v_add_f32_e32 v29, 1.0, v29
	v_rcp_f32_e32 v29, v29
	v_mul_f32_e32 v28, v20, v28
	v_mul_f32_e32 v31, v21, v31
	v_mul_f32_e32 v31, v31, v35
	v_mul_f32_e32 v28, v28, v29
	v_cvt_pk_bf16_f32 v42, v28, v31
	v_cvt_pk_bf16_f32 v43, v30, v34
	v_cvt_pk_bf16_f32 v28, v12, v13
	s_nop 0
	v_cvt_pk_bf16_f32 v28, v14, v15
	v_cvt_pk_bf16_f32 v20, v20, v21
	s_nop 0
	v_cvt_pk_bf16_f32 v20, v22, v23
	s_nop 0
	v_or_b32_e32 v20, 32, v60
	v_mad_i64_i32 v[20:21], s[16:17], v20, s78, v[38:39]
	v_lshl_add_u64 v[20:21], v[20:21], 0, v[154:155]
	global_store_dwordx4 v[20:21], v[40:43], off
	v_cndmask_b32_e64 v20, v16, v24, s[6:7]
	v_cndmask_b32_e64 v21, v16, v24, s[8:9]
	s_nop 1
	v_mov_b32_dpp v91, v20 row_ror:1 row_mask:0xf bank_mask:0xf
	v_mov_b32_dpp v22, v21 row_ror:2 row_mask:0xf bank_mask:0xf
	v_cndmask_b32_e64 v20, v17, v25, s[6:7]
	v_cndmask_b32_e64 v21, v17, v25, s[8:9]
	s_nop 1
	v_mov_b32_dpp v153, v20 row_ror:1 row_mask:0xf bank_mask:0xf
	v_mov_b32_dpp v23, v21 row_ror:2 row_mask:0xf bank_mask:0xf
	v_cndmask_b32_e64 v20, v19, v27, s[6:7]
	v_cndmask_b32_e64 v21, v19, v27, s[8:9]
	s_nop 1
	v_mov_b32_dpp v151, v20 row_ror:1 row_mask:0xf bank_mask:0xf
	v_mov_b32_dpp v24, v21 row_ror:2 row_mask:0xf bank_mask:0xf
	v_mov_b32_e32 v20, v19
	v_mov_b32_e32 v21, v97
	v_cndmask_b32_e64 v25, v18, v26, s[6:7]
	s_waitcnt lgkmcnt(1)
; __device__ __forceinline__ unsigned cvt_pk_bf16(float lo, float hi) { unsigned r; asm volatile("v_cvt_pk_bf16_f32 %0, %1, %2" : "=v"(r) : "v"(lo), "v"(hi)); return r; }
;     __device__ __forceinline__ void operator()(const f32x4 (&acc)[2][2][4][2], const Unit& u, int wr, int wc, int fr, int fq) const {
;     ...
;                     const f32x4 g = acc[ai][0][m][n], uu = acc[ai][1][m][n], gp = acc[ai][0][m > 0 ? m - 1 : 0][n];
;                     f32x4 r;
; #pragma unroll
;                     for (int e = 0; e < 4; ++e) {
;                         const float s1 = (fr == 15) ? gp[e] : g[e], s2 = (fr >= 14) ? gp[e] : g[e];
;                         const float p1 = __int_as_float(__builtin_amdgcn_ds_bpermute(src1, __float_as_int(s1))), p2 = __int_as_float(__builtin_amdgcn_ds_bpermute(src2, __float_as_int(s2)));
;                         const float c = bb[n][e] + w0[n][e] * p2 + w1[n][e] * p1 + w2[n][e] * g[e];
;                         r[e] = c * uu[e] * __builtin_amdgcn_rcpf(1.0f + __builtin_amdgcn_exp2f(c * -1.4426950408889634f));
;                     }
;                     if (n == 0) { wa.x = cvt_pk_bf16(r[0], r[1]); wa.y = cvt_pk_bf16(r[2], r[3]); wg.x = cvt_pk_bf16(g[0], g[1]); wg.y = cvt_pk_bf16(g[2], g[3]); wu.x = cvt_pk_bf16(uu[0], uu[1]); wu.y = cvt_pk_bf16(uu[2], uu[3]); }
;                     else { wa.z = cvt_pk_bf16(r[0], r[1]); wa.w = cvt_pk_bf16(r[2], r[3]); wg.z = cvt_pk_bf16(g[0], g[1]); wg.w = cvt_pk_bf16(g[2], g[3]); wu.z = cvt_pk_bf16(uu[0], uu[1]); wu.w = cvt_pk_bf16(uu[2], uu[3]); }
;                 }
;                 if (m == 0 && fr < 2) {
;                     *(u32x4*)(hg + (size_t)(blk * 4 + 2 + fr) * dff + f0) = wg; *(u32x4*)(hu + (size_t)(blk * 2 + fr) * dff + f0) = wu;
;                 } else {
;                     *(u32x4*)(act + (size_t)(rowb + m * 16 + fr) * dff + f0) = wa;
;                 }
;                 if (m == 3 && fr >= 14) *(u32x4*)(hg + (size_t)(blk * 4 + fr - 14) * dff + f0) = wg;
	v_pk_mul_f32 v[20:21], v[20:21], v[150:151]
	s_waitcnt lgkmcnt(0)
	v_fma_f32 v24, v89, v24, v105
	v_add_f32_e32 v21, v21, v24
	v_add_f32_e32 v24, v20, v21
	v_mul_f32_e32 v20, 0xbfb8aa3b, v24
	v_exp_f32_e32 v20, v20
	v_cndmask_b32_e64 v21, v18, v26, s[8:9]
	v_mov_b32_dpp v93, v25 row_ror:1 row_mask:0xf bank_mask:0xf
	s_nop 1
	v_mov_b32_dpp v25, v21 row_ror:2 row_mask:0xf bank_mask:0xf
	v_add_f32_e32 v20, 1.0, v20
	v_rcp_f32_e32 v26, v20
	v_mov_b32_e32 v20, v18
	v_mov_b32_e32 v21, v96
	s_waitcnt lgkmcnt(1)
	v_pk_mul_f32 v[20:21], v[20:21], v[92:93]
	s_waitcnt lgkmcnt(0)
	v_fma_f32 v25, v88, v25, v104
	v_add_f32_e32 v21, v21, v25
	v_add_f32_e32 v20, v20, v21
	v_mul_f32_e32 v21, 0xbfb8aa3b, v20
	v_exp_f32_e32 v21, v21
	v_mul_f32_e32 v24, v11, v24
	v_mul_f32_e32 v25, v10, v20
	v_mul_f32_e32 v24, v24, v26
	v_add_f32_e32 v20, 1.0, v21
	v_rcp_f32_e32 v26, v20
	v_mov_b32_e32 v20, v17
	v_mov_b32_e32 v21, v95
	v_pk_mul_f32 v[20:21], v[20:21], v[152:153]
	v_fma_f32 v23, v87, v23, v103
	v_add_f32_e32 v21, v21, v23
	v_add_f32_e32 v23, v20, v21
	v_mul_f32_e32 v20, 0xbfb8aa3b, v23
	v_exp_f32_e32 v27, v20
	v_mov_b32_e32 v20, v16
	v_mov_b32_e32 v21, v94
	v_pk_mul_f32 v[20:21], v[20:21], v[90:91]
	v_fmac_f32_e32 v102, v86, v22
	v_add_f32_e32 v21, v21, v102
	v_add_f32_e32 v20, v20, v21
	v_mul_f32_e32 v21, 0xbfb8aa3b, v20
	v_exp_f32_e32 v21, v21
	v_mul_f32_e32 v22, v25, v26
	v_add_f32_e32 v25, 1.0, v27
	v_rcp_f32_e32 v25, v25
	v_add_f32_e32 v21, 1.0, v21
	v_rcp_f32_e32 v21, v21
	v_mul_f32_e32 v20, v8, v20
	v_mul_f32_e32 v23, v9, v23
	v_mul_f32_e32 v23, v23, v25
	v_mul_f32_e32 v20, v20, v21
	v_cvt_pk_bf16_f32 v20, v20, v23
	v_cvt_pk_bf16_f32 v21, v22, v24
	v_cvt_pk_bf16_f32 v16, v16, v17
	v_cvt_pk_bf16_f32 v17, v18, v19
	v_cvt_pk_bf16_f32 v8, v8, v9
	v_cndmask_b32_e64 v9, v4, v12, s[8:9]
	v_cvt_pk_bf16_f32 v8, v10, v11
	s_nop 1
	v_mov_b32_dpp v10, v9 row_ror:2 row_mask:0xf bank_mask:0xf
	v_cndmask_b32_e64 v8, v4, v12, s[6:7]
	s_nop 1
	v_mov_b32_dpp v75, v8 row_ror:1 row_mask:0xf bank_mask:0xf
	v_cndmask_b32_e64 v8, v5, v13, s[6:7]
	v_cndmask_b32_e64 v9, v5, v13, s[8:9]
	s_nop 1
	v_mov_b32_dpp v145, v8 row_ror:1 row_mask:0xf bank_mask:0xf
	v_mov_b32_dpp v11, v9 row_ror:2 row_mask:0xf bank_mask:0xf
	v_cndmask_b32_e64 v8, v7, v15, s[6:7]
	v_cndmask_b32_e64 v9, v7, v15, s[8:9]
	s_nop 1
	v_mov_b32_dpp v143, v8 row_ror:1 row_mask:0xf bank_mask:0xf
	v_mov_b32_dpp v12, v9 row_ror:2 row_mask:0xf bank_mask:0xf
	v_mov_b32_e32 v8, v7
	v_mov_b32_e32 v9, v81
	v_cndmask_b32_e64 v13, v6, v14, s[6:7]
	s_waitcnt lgkmcnt(1)
	v_pk_mul_f32 v[8:9], v[8:9], v[142:143]
	s_waitcnt lgkmcnt(0)
	v_fma_f32 v12, v69, v12, v73
	v_add_f32_e32 v9, v9, v12
	v_add_f32_e32 v12, v8, v9
	v_mul_f32_e32 v8, 0xbfb8aa3b, v12
	v_exp_f32_e32 v8, v8
	v_cndmask_b32_e64 v9, v6, v14, s[8:9]
	v_mov_b32_dpp v77, v13 row_ror:1 row_mask:0xf bank_mask:0xf
	s_nop 1
	v_mov_b32_dpp v13, v9 row_ror:2 row_mask:0xf bank_mask:0xf
	v_add_f32_e32 v8, 1.0, v8
	v_rcp_f32_e32 v14, v8
	v_mov_b32_e32 v8, v6
	v_mov_b32_e32 v9, v80
	s_waitcnt lgkmcnt(1)
	v_pk_mul_f32 v[8:9], v[8:9], v[76:77]
	s_waitcnt lgkmcnt(0)
	v_fma_f32 v13, v68, v13, v72
	v_add_f32_e32 v9, v9, v13
	v_add_f32_e32 v8, v8, v9
	v_mul_f32_e32 v9, 0xbfb8aa3b, v8
	v_exp_f32_e32 v9, v9
	v_mul_f32_e32 v12, v3, v12
	v_mul_f32_e32 v13, v2, v8
	v_mul_f32_e32 v12, v12, v14
	v_add_f32_e32 v8, 1.0, v9
	v_rcp_f32_e32 v14, v8
	v_mov_b32_e32 v8, v5
	v_mov_b32_e32 v9, v79
	v_pk_mul_f32 v[8:9], v[8:9], v[144:145]
	v_fma_f32 v11, v67, v11, v71
	v_add_f32_e32 v9, v9, v11
	v_add_f32_e32 v11, v8, v9
	v_mul_f32_e32 v8, 0xbfb8aa3b, v11
	v_exp_f32_e32 v15, v8
	v_mov_b32_e32 v8, v4
	v_mov_b32_e32 v9, v78
	v_pk_mul_f32 v[8:9], v[8:9], v[74:75]
	v_fmac_f32_e32 v70, v66, v10
	v_add_f32_e32 v9, v9, v70
	v_add_f32_e32 v8, v8, v9
	v_mul_f32_e32 v9, 0xbfb8aa3b, v8
	v_exp_f32_e32 v9, v9
	v_mul_f32_e32 v10, v13, v14
	v_add_f32_e32 v13, 1.0, v15
	v_rcp_f32_e32 v13, v13
	v_add_f32_e32 v9, 1.0, v9
	v_rcp_f32_e32 v9, v9
	v_mul_f32_e32 v11, v1, v11
	v_mul_f32_e32 v8, v0, v8
	v_mul_f32_e32 v11, v11, v13
	v_mul_f32_e32 v8, v8, v9
	v_cvt_pk_bf16_f32 v22, v8, v11
	v_cvt_pk_bf16_f32 v23, v10, v12
	v_cvt_pk_bf16_f32 v18, v4, v5
	v_cvt_pk_bf16_f32 v19, v6, v7
	v_cvt_pk_bf16_f32 v0, v0, v1
	s_nop 0
	v_cvt_pk_bf16_f32 v0, v2, v3
	s_nop 0
	v_or_b32_e32 v0, 48, v60
	v_mad_i64_i32 v[0:1], s[16:17], v0, s78, v[38:39]
	v_lshl_add_u64 v[0:1], v[0:1], 0, v[154:155]
	global_store_dwordx4 v[0:1], v[20:23], off
	s_and_saveexec_b64 s[56:57], s[8:9]
	s_cbranch_execz .LBB0_494
	v_add_u32_e32 v2, s45, v214
	v_mov_b64_e32 v[0:1], s[28:29]
	v_mad_i64_i32 v[0:1], s[16:17], v2, s78, v[0:1]
	v_lshl_add_u64 v[0:1], v[196:197], 1, v[0:1]
	global_store_dwordx4 v[0:1], v[16:19], off
